# row-max chains: redundant canonicalizing v_max pairs collapsed to one v_max at 6 sites (bit-identical), on top of the previous version
# speedup vs baseline: 1.0072x; 1.0033x over previous
; #define SBAR() __builtin_amdgcn_sched_barrier(0)
; #define LW(n) asm volatile("s_waitcnt lgkmcnt(" #n ")" ::: "memory")
; template <int MODE, bool PF> __device__ __forceinline__ void pv_partial(f32x16* o, int vb, bf16x8 pa0, bf16x8 pa1, bf16x8 pa2, bf16x8 pa3, f32x16& p0, f32x16& p1, float& m_reg, float& alpha) {
;     VFrag fa, fb;
;     v_frag_read<0>(fa, vb);
;     if constexpr (PF) { v_frag_read<1>(fb, vb); LW(8); } else LW(0);
;     SBAR();
;     pv_mma(o[0], fa, pa0, pa1, pa2, pa3);
;     float pm0 = p0[0];
; #pragma unroll
;     for (int r = 1; r < 16; ++r) pm0 = fmaxf(pm0, p0[r]);
;     if constexpr (PF) { v_frag_read<2>(fa, vb); LW(8); } else { v_frag_read<1>(fb, vb); LW(0); }
;     SBAR();
;     pv_mma(o[1], fb, pa0, pa1, pa2, pa3);
;     float pmax = pm0;
; #pragma unroll
;     for (int r = 0; r < 16; ++r) pmax = fmaxf(pmax, p1[r]);
;     { auto rr = __builtin_amdgcn_permlane32_swap(__float_as_uint(pmax), __float_as_uint(pmax), false, false);
;       pmax = fmaxf(__uint_as_float(rr[0]), __uint_as_float(rr[1])); }
;     const float mn = (pmax - m_reg > Cst<MODE>::THRS) ? fmaxf(m_reg, pmax) : m_reg;
;     alpha = __builtin_amdgcn_exp2f(m_reg - mn); m_reg = mn;
;     const f32x16 mnv = {mn, mn, mn, mn, mn, mn, mn, mn, mn, mn, mn, mn, mn, mn, mn, mn};
.LBB0_545:
	v_add_u32_e32 v163, s93, v170
	ds_read_b64_tr_b16 v[64:65], v163 offset:0
	ds_read_b64_tr_b16 v[66:67], v163 offset:0x800
	ds_read_b64_tr_b16 v[68:69], v163 offset:0x1000
	ds_read_b64_tr_b16 v[70:71], v163 offset:0x1800
	ds_read_b64_tr_b16 v[88:89], v163 offset:0x2000
	ds_read_b64_tr_b16 v[90:91], v163 offset:0x2800
	ds_read_b64_tr_b16 v[92:93], v163 offset:0x3000
	ds_read_b64_tr_b16 v[94:95], v163 offset:0x3800
	ds_read_b64_tr_b16 v[188:189], v163 offset:0x200
	ds_read_b64_tr_b16 v[190:191], v163 offset:0xa00
	ds_read_b64_tr_b16 v[192:193], v163 offset:0x1200
	ds_read_b64_tr_b16 v[194:195], v163 offset:0x1a00
	ds_read_b64_tr_b16 v[200:201], v163 offset:0x2200
	ds_read_b64_tr_b16 v[202:203], v163 offset:0x2a00
	ds_read_b64_tr_b16 v[204:205], v163 offset:0x3200
	ds_read_b64_tr_b16 v[206:207], v163 offset:0x3a00
	s_waitcnt lgkmcnt(8)
	s_nop 0
	v_mfma_f32_32x32x16_bf16 v[16:31], v[84:87], v[64:67], v[16:31]
	v_max_f32_e32 v64, v96, v97
	v_max3_f32 v64, v64, v98, v99
	v_max3_f32 v64, v64, v100, v101
	v_max3_f32 v64, v64, v102, v103
	v_max3_f32 v64, v64, v104, v105
	v_mfma_f32_32x32x16_bf16 v[16:31], v[72:75], v[68:71], v[16:31]
	v_max3_f32 v64, v64, v106, v107
	v_max3_f32 v64, v64, v108, v109
	v_max3_f32 v185, v64, v110, v111
	ds_read_b64_tr_b16 v[64:65], v163 offset:0x400
	ds_read_b64_tr_b16 v[66:67], v163 offset:0xc00
	ds_read_b64_tr_b16 v[68:69], v163 offset:0x1400
	ds_read_b64_tr_b16 v[70:71], v163 offset:0x1c00
	v_mfma_f32_32x32x16_bf16 v[16:31], v[76:79], v[88:91], v[16:31]
	ds_read_b64_tr_b16 v[88:89], v163 offset:0x2400
	ds_read_b64_tr_b16 v[90:91], v163 offset:0x2c00
	v_mfma_f32_32x32x16_bf16 v[16:31], v[80:83], v[92:95], v[16:31]
	ds_read_b64_tr_b16 v[92:93], v163 offset:0x3400
	ds_read_b64_tr_b16 v[94:95], v163 offset:0x3c00
	s_waitcnt lgkmcnt(8)
	v_mfma_f32_32x32x16_bf16 v[48:63], v[84:87], v[188:191], v[48:63]
	v_max3_f32 v185, v185, v112, v113
	v_max3_f32 v185, v185, v114, v115
	v_max3_f32 v185, v185, v116, v117
	v_max3_f32 v185, v185, v118, v119
	v_max3_f32 v185, v185, v120, v121
	v_max3_f32 v185, v185, v122, v123
	v_max3_f32 v185, v185, v124, v125
	v_mfma_f32_32x32x16_bf16 v[48:63], v[72:75], v[192:195], v[48:63]
	v_max3_f32 v185, v185, v126, v127
	v_mov_b32_e32 v188, v185
	s_nop 1
	v_permlane32_swap_b32_e32 v185, v188
	ds_read_b64_tr_b16 v[190:191], v163 offset:0x600
	v_mfma_f32_32x32x16_bf16 v[48:63], v[76:79], v[200:203], v[48:63]
	v_max_f32_e32 v185, v185, v188
	ds_read_b64_tr_b16 v[192:193], v163 offset:0xe00
	v_cmp_lt_f32_e32 vcc, s72, v185
	ds_read_b64_tr_b16 v[194:195], v163 offset:0x1600
	ds_read_b64_tr_b16 v[196:197], v163 offset:0x1e00
	v_mfma_f32_32x32x16_bf16 v[48:63], v[80:83], v[204:207], v[48:63]
	ds_read_b64_tr_b16 v[200:201], v163 offset:0x2600
	v_cndmask_b32_e32 v186, 0, v185, vcc
	ds_read_b64_tr_b16 v[202:203], v163 offset:0x2e00
	ds_read_b64_tr_b16 v[204:205], v163 offset:0x3600
	v_exp_f32_e64 v188, -v186
	s_cbranch_vccnz .Lda_rare1

; #define SBAR() __builtin_amdgcn_sched_barrier(0)
; #define LW(n) asm volatile("s_waitcnt lgkmcnt(" #n ")" ::: "memory")
; template <int MODE, bool PF> __device__ __forceinline__ void pv_partial(f32x16* o, int vb, bf16x8 pa0, bf16x8 pa1, bf16x8 pa2, bf16x8 pa3, f32x16& p0, f32x16& p1, float& m_reg, float& alpha) {
;     VFrag fa, fb;
;     v_frag_read<0>(fa, vb);
;     if constexpr (PF) { v_frag_read<1>(fb, vb); LW(8); } else LW(0);
;     SBAR();
;     pv_mma(o[0], fa, pa0, pa1, pa2, pa3);
;     float pm0 = p0[0];
; #pragma unroll
;     for (int r = 1; r < 16; ++r) pm0 = fmaxf(pm0, p0[r]);
;     if constexpr (PF) { v_frag_read<2>(fa, vb); LW(8); } else { v_frag_read<1>(fb, vb); LW(0); }
;     SBAR();
;     pv_mma(o[1], fb, pa0, pa1, pa2, pa3);
;     float pmax = pm0;
; #pragma unroll
;     for (int r = 0; r < 16; ++r) pmax = fmaxf(pmax, p1[r]);
;     { auto rr = __builtin_amdgcn_permlane32_swap(__float_as_uint(pmax), __float_as_uint(pmax), false, false);
;       pmax = fmaxf(__uint_as_float(rr[0]), __uint_as_float(rr[1])); }
;     const float mn = (pmax - m_reg > Cst<MODE>::THRS) ? fmaxf(m_reg, pmax) : m_reg;
;     alpha = __builtin_amdgcn_exp2f(m_reg - mn); m_reg = mn;
;     const f32x16 mnv = {mn, mn, mn, mn, mn, mn, mn, mn, mn, mn, mn, mn, mn, mn, mn, mn};
.LBB0_557:
	v_add_u32_e32 v126, s31, v170
	ds_read_b64_tr_b16 v[64:65], v126 offset:0
	ds_read_b64_tr_b16 v[66:67], v126 offset:0x800
	ds_read_b64_tr_b16 v[68:69], v126 offset:0x1000
	ds_read_b64_tr_b16 v[70:71], v126 offset:0x1800
	ds_read_b64_tr_b16 v[122:123], v126 offset:0x2000
	ds_read_b64_tr_b16 v[124:125], v126 offset:0x2800
	ds_read_b64_tr_b16 v[190:191], v126 offset:0x3000
	ds_read_b64_tr_b16 v[192:193], v126 offset:0x3800
	ds_read_b64_tr_b16 v[194:195], v126 offset:0x200
	ds_read_b64_tr_b16 v[196:197], v126 offset:0xa00
	ds_read_b64_tr_b16 v[200:201], v126 offset:0x1200
	ds_read_b64_tr_b16 v[202:203], v126 offset:0x1a00
	ds_read_b64_tr_b16 v[204:205], v126 offset:0x2200
	ds_read_b64_tr_b16 v[206:207], v126 offset:0x2a00
	ds_read_b64_tr_b16 v[208:209], v126 offset:0x3200
	ds_read_b64_tr_b16 v[210:211], v126 offset:0x3a00
	s_waitcnt lgkmcnt(8)
	s_nop 0
	v_mfma_f32_32x32x16_bf16 v[16:31], v[116:119], v[64:67], v[16:31]
	v_max_f32_e32 v64, v96, v97
	v_max3_f32 v64, v64, v98, v99
	v_max3_f32 v64, v64, v100, v101
	v_max3_f32 v64, v64, v102, v103
	v_max3_f32 v64, v64, v104, v105
	v_mfma_f32_32x32x16_bf16 v[16:31], v[72:75], v[68:71], v[16:31]
	v_max3_f32 v64, v64, v106, v107
	v_max3_f32 v64, v64, v108, v109
	v_max3_f32 v127, v64, v110, v111
	ds_read_b64_tr_b16 v[64:65], v126 offset:0x400
	ds_read_b64_tr_b16 v[66:67], v126 offset:0xc00
	ds_read_b64_tr_b16 v[68:69], v126 offset:0x1400
	ds_read_b64_tr_b16 v[70:71], v126 offset:0x1c00
	v_mfma_f32_32x32x16_bf16 v[16:31], v[76:79], v[122:125], v[16:31]
	ds_read_b64_tr_b16 v[122:123], v126 offset:0x2400
	ds_read_b64_tr_b16 v[124:125], v126 offset:0x2c00
	v_mfma_f32_32x32x16_bf16 v[16:31], v[112:115], v[190:193], v[16:31]
	ds_read_b64_tr_b16 v[190:191], v126 offset:0x3400
	ds_read_b64_tr_b16 v[192:193], v126 offset:0x3c00
	s_waitcnt lgkmcnt(8)
	v_mfma_f32_32x32x16_bf16 v[48:63], v[116:119], v[194:197], v[48:63]
	v_max3_f32 v127, v127, v80, v81
	v_max3_f32 v127, v127, v82, v83
	v_max3_f32 v127, v127, v84, v85
	v_max3_f32 v127, v127, v86, v87
	v_max3_f32 v127, v127, v88, v89
	v_max3_f32 v127, v127, v90, v91
	v_max3_f32 v127, v127, v92, v93
	v_mfma_f32_32x32x16_bf16 v[48:63], v[72:75], v[200:203], v[48:63]
	v_max3_f32 v127, v127, v94, v95
	v_mov_b32_e32 v186, v127
	s_nop 1
	v_permlane32_swap_b32_e32 v127, v186
	ds_read_b64_tr_b16 v[194:195], v126 offset:0x600
	v_mfma_f32_32x32x16_bf16 v[48:63], v[76:79], v[204:207], v[48:63]
	v_max_f32_e32 v127, v127, v186
	ds_read_b64_tr_b16 v[196:197], v126 offset:0xe00
	v_cmp_lt_f32_e32 vcc, s72, v127
	ds_read_b64_tr_b16 v[200:201], v126 offset:0x1600
	ds_read_b64_tr_b16 v[202:203], v126 offset:0x1e00
	v_mfma_f32_32x32x16_bf16 v[48:63], v[112:115], v[208:211], v[48:63]
	ds_read_b64_tr_b16 v[204:205], v126 offset:0x2600
	v_cndmask_b32_e32 v186, 0, v127, vcc
	ds_read_b64_tr_b16 v[206:207], v126 offset:0x2e00
	ds_read_b64_tr_b16 v[208:209], v126 offset:0x3600
	v_exp_f32_e64 v185, -v186
	s_cbranch_vccnz .Lda_rare2

; #define SBAR() __builtin_amdgcn_sched_barrier(0)
; #define LW(n) asm volatile("s_waitcnt lgkmcnt(" #n ")" ::: "memory")
; template <int MODE, bool PF> __device__ __forceinline__ void pv_partial(f32x16* o, int vb, bf16x8 pa0, bf16x8 pa1, bf16x8 pa2, bf16x8 pa3, f32x16& p0, f32x16& p1, float& m_reg, float& alpha) {
;     VFrag fa, fb;
;     v_frag_read<0>(fa, vb);
;     if constexpr (PF) { v_frag_read<1>(fb, vb); LW(8); } else LW(0);
;     SBAR();
;     pv_mma(o[0], fa, pa0, pa1, pa2, pa3);
;     float pm0 = p0[0];
; #pragma unroll
;     for (int r = 1; r < 16; ++r) pm0 = fmaxf(pm0, p0[r]);
;     if constexpr (PF) { v_frag_read<2>(fa, vb); LW(8); } else { v_frag_read<1>(fb, vb); LW(0); }
;     SBAR();
;     pv_mma(o[1], fb, pa0, pa1, pa2, pa3);
;     float pmax = pm0;
; #pragma unroll
;     for (int r = 0; r < 16; ++r) pmax = fmaxf(pmax, p1[r]);
;     { auto rr = __builtin_amdgcn_permlane32_swap(__float_as_uint(pmax), __float_as_uint(pmax), false, false);
;       pmax = fmaxf(__uint_as_float(rr[0]), __uint_as_float(rr[1])); }
;     const float mn = (pmax - m_reg > Cst<MODE>::THRS) ? fmaxf(m_reg, pmax) : m_reg;
;     alpha = __builtin_amdgcn_exp2f(m_reg - mn); m_reg = mn;
;     const f32x16 mnv = {mn, mn, mn, mn, mn, mn, mn, mn, mn, mn, mn, mn, mn, mn, mn, mn};
;     if constexpr (PF) { v_frag_read<3>(fb, vb); LW(8); } else { v_frag_read<2>(fa, vb); LW(0); }
;     SBAR();
;     pv_mma(o[2], fa, pa0, pa1, pa2, pa3);
;     p0 = p0 - mnv; p1 = p1 - mnv;
; #pragma unroll
;     for (int r = 0; r < 8; ++r) p0[r] = __builtin_amdgcn_exp2f(p0[r]);
;     if constexpr (PF) { LW(0); } else { v_frag_read<3>(fb, vb); LW(0); }
;     SBAR();
;     pv_mma(o[3], fb, pa0, pa1, pa2, pa3);
; #pragma unroll
;     for (int r = 8; r < 16; ++r) p0[r] = __builtin_amdgcn_exp2f(p0[r]);
;     asm volatile("" : "+v"(p0), "+v"(p1));
; }
.LBB0_575:
	v_add_u32_e32 v146, s92, v170
	ds_read_b64_tr_b16 v[64:65], v146 offset:0
	ds_read_b64_tr_b16 v[66:67], v146 offset:0x800
	ds_read_b64_tr_b16 v[68:69], v146 offset:0x1000
	ds_read_b64_tr_b16 v[70:71], v146 offset:0x1800
	ds_read_b64_tr_b16 v[80:81], v146 offset:0x2000
	ds_read_b64_tr_b16 v[82:83], v146 offset:0x2800
	ds_read_b64_tr_b16 v[84:85], v146 offset:0x3000
	ds_read_b64_tr_b16 v[86:87], v146 offset:0x3800
	ds_read_b64_tr_b16 v[88:89], v146 offset:0x200
	ds_read_b64_tr_b16 v[90:91], v146 offset:0xa00
	ds_read_b64_tr_b16 v[92:93], v146 offset:0x1200
	ds_read_b64_tr_b16 v[94:95], v146 offset:0x1a00
	ds_read_b64_tr_b16 v[138:139], v146 offset:0x2200
	ds_read_b64_tr_b16 v[140:141], v146 offset:0x2a00
	ds_read_b64_tr_b16 v[152:153], v146 offset:0x3200
	ds_read_b64_tr_b16 v[154:155], v146 offset:0x3a00
	s_waitcnt lgkmcnt(8)
	s_nop 0
	v_mfma_f32_32x32x16_bf16 v[16:31], v[132:135], v[64:67], v[16:31]
	v_max_f32_e32 v64, v96, v97
	v_max3_f32 v64, v64, v98, v99
	v_max3_f32 v64, v64, v100, v101
	v_max3_f32 v64, v64, v102, v103
	v_max3_f32 v64, v64, v104, v105
	v_mfma_f32_32x32x16_bf16 v[16:31], v[72:75], v[68:71], v[16:31]
	v_max3_f32 v64, v64, v106, v107
	v_max3_f32 v66, v64, v108, v109
	ds_read_b64_tr_b16 v[64:65], v146 offset:0x400
	v_max3_f32 v142, v66, v110, v111
	ds_read_b64_tr_b16 v[66:67], v146 offset:0xc00
	ds_read_b64_tr_b16 v[68:69], v146 offset:0x1400
	ds_read_b64_tr_b16 v[70:71], v146 offset:0x1c00
	v_mfma_f32_32x32x16_bf16 v[16:31], v[76:79], v[80:83], v[16:31]
	ds_read_b64_tr_b16 v[80:81], v146 offset:0x2400
	ds_read_b64_tr_b16 v[82:83], v146 offset:0x2c00
	ds_read_b64_tr_b16 v[156:157], v146 offset:0x3400
	ds_read_b64_tr_b16 v[158:159], v146 offset:0x3c00
	s_waitcnt lgkmcnt(8)
	v_mfma_f32_32x32x16_bf16 v[16:31], v[128:131], v[84:87], v[16:31]
	v_mfma_f32_32x32x16_bf16 v[48:63], v[132:135], v[88:91], v[48:63]
	v_max3_f32 v84, v142, v112, v113
	v_max3_f32 v84, v84, v114, v115
	v_max3_f32 v84, v84, v116, v117
	v_max3_f32 v84, v84, v118, v119
	v_max3_f32 v84, v84, v120, v121
	v_max3_f32 v84, v84, v122, v123
	v_max3_f32 v84, v84, v124, v125
	v_mfma_f32_32x32x16_bf16 v[48:63], v[72:75], v[92:95], v[48:63]
	v_max3_f32 v84, v84, v126, v127
	v_mov_b32_e32 v85, v84
	s_nop 1
	v_permlane32_swap_b32_e32 v84, v85
	v_max_f32_e32 v85, v85, v85
	v_max_f32_e32 v84, v84, v84
	v_max_f32_e32 v84, v84, v85
	v_mfma_f32_32x32x16_bf16 v[48:63], v[76:79], v[138:141], v[48:63]
	ds_read_b64_tr_b16 v[140:141], v146 offset:0x600
	ds_read_b64_tr_b16 v[142:143], v146 offset:0xe00
	ds_read_b64_tr_b16 v[170:171], v146 offset:0x1600
	v_sub_f32_e32 v85, v84, v186
	v_max_f32_e32 v86, v186, v186
	ds_read_b64_tr_b16 v[172:173], v146 offset:0x1e00
	v_max_f32_e32 v84, v86, v84
	v_mfma_f32_32x32x16_bf16 v[48:63], v[128:131], v[152:155], v[48:63]
	v_cmp_lt_f32_e32 vcc, s72, v85
	ds_read_b64_tr_b16 v[174:175], v146 offset:0x2600
	ds_read_b64_tr_b16 v[176:177], v146 offset:0x2e00
	ds_read_b64_tr_b16 v[152:153], v146 offset:0x3600
	ds_read_b64_tr_b16 v[154:155], v146 offset:0x3e00
	s_waitcnt lgkmcnt(8)
	s_nop 1
	v_cndmask_b32_e32 v160, v186, v84, vcc
	v_sub_f32_e32 v84, v186, v160
	v_exp_f32_e32 v138, v84
	v_mfma_f32_32x32x16_bf16 v[32:47], v[132:135], v[64:67], v[32:47]
	v_sub_f32_e32 v103, v103, v160
	v_sub_f32_e32 v102, v102, v160
	v_sub_f32_e32 v101, v101, v160
	v_sub_f32_e32 v100, v100, v160
	v_sub_f32_e32 v67, v99, v160
	v_sub_f32_e32 v66, v98, v160
	v_sub_f32_e32 v65, v97, v160
	v_mfma_f32_32x32x16_bf16 v[32:47], v[72:75], v[68:71], v[32:47]
	v_sub_f32_e32 v64, v96, v160
	v_exp_f32_e32 v64, v64
	v_exp_f32_e32 v65, v65
	v_exp_f32_e32 v66, v66
	v_exp_f32_e32 v67, v67
	v_exp_f32_e32 v68, v100
	v_exp_f32_e32 v69, v101
	v_mfma_f32_32x32x16_bf16 v[32:47], v[76:79], v[80:83], v[32:47]
	v_exp_f32_e32 v70, v102
	v_exp_f32_e32 v71, v103
	s_waitcnt lgkmcnt(0)
	v_sub_f32_e32 v95, v127, v160
	v_sub_f32_e32 v94, v126, v160
	v_sub_f32_e32 v93, v125, v160
	v_sub_f32_e32 v92, v124, v160
	v_mfma_f32_32x32x16_bf16 v[32:47], v[128:131], v[156:159], v[32:47]
	v_sub_f32_e32 v91, v123, v160
	v_sub_f32_e32 v90, v122, v160
	v_sub_f32_e32 v89, v121, v160
	v_sub_f32_e32 v88, v120, v160
	v_sub_f32_e32 v87, v119, v160
	v_sub_f32_e32 v86, v118, v160
	v_sub_f32_e32 v85, v117, v160
	v_sub_f32_e32 v84, v116, v160
	v_sub_f32_e32 v83, v115, v160
	v_sub_f32_e32 v82, v114, v160
	v_sub_f32_e32 v81, v113, v160
	v_sub_f32_e32 v80, v112, v160
	v_sub_f32_e32 v111, v111, v160
	v_sub_f32_e32 v110, v110, v160
	v_sub_f32_e32 v109, v109, v160
	v_sub_f32_e32 v108, v108, v160
	v_sub_f32_e32 v107, v107, v160
	v_sub_f32_e32 v106, v106, v160
	v_sub_f32_e32 v105, v105, v160
	v_sub_f32_e32 v104, v104, v160
	v_mfma_f32_32x32x16_bf16 v[0:15], v[132:135], v[140:143], v[0:15]
	v_cmp_gt_f32_e32 vcc, 1.0, v138
	v_mfma_f32_32x32x16_bf16 v[0:15], v[72:75], v[170:173], v[0:15]
	v_exp_f32_e32 v72, v104
	v_exp_f32_e32 v73, v105
	v_exp_f32_e32 v74, v106
	v_exp_f32_e32 v75, v107
	v_mfma_f32_32x32x16_bf16 v[0:15], v[76:79], v[174:177], v[0:15]
	v_exp_f32_e32 v76, v108
	v_exp_f32_e32 v77, v109
	v_exp_f32_e32 v78, v110
	v_exp_f32_e32 v79, v111
	v_mfma_f32_32x32x16_bf16 v[0:15], v[128:131], v[152:155], v[0:15]
	s_cbranch_vccz .LBB0_579
	s_and_saveexec_b64 s[2:3], s[0:1]
	ds_write_b32 v168, v138 offset:128
	s_or_b64 exec, exec, s[2:3]
	s_waitcnt lgkmcnt(0)
	v_add_u32_e32 v108, s19, v148
	ds_read_b128 v[96:99], v108 offset:224
	ds_read_b128 v[100:103], v108 offset:192
	ds_read_b128 v[104:107], v108 offset:160
	ds_read_b128 v[108:111], v108 offset:128
	s_waitcnt lgkmcnt(0)
	v_pk_mul_f32 v[28:29], v[28:29], v[96:97]
	v_pk_mul_f32 v[24:25], v[24:25], v[100:101]
	v_pk_mul_f32 v[20:21], v[20:21], v[104:105]
	v_pk_mul_f32 v[30:31], v[30:31], v[98:99]
	v_pk_mul_f32 v[26:27], v[26:27], v[102:103]
	v_pk_mul_f32 v[22:23], v[22:23], v[106:107]
	v_pk_mul_f32 v[18:19], v[18:19], v[110:111]
	v_pk_mul_f32 v[16:17], v[16:17], v[108:109]
	v_pk_mul_f32 v[60:61], v[60:61], v[96:97]
	v_pk_mul_f32 v[56:57], v[56:57], v[100:101]
	v_pk_mul_f32 v[52:53], v[52:53], v[104:105]
	v_pk_mul_f32 v[62:63], v[62:63], v[98:99]
	v_pk_mul_f32 v[58:59], v[58:59], v[102:103]
	v_pk_mul_f32 v[54:55], v[54:55], v[106:107]
	v_pk_mul_f32 v[50:51], v[50:51], v[110:111]
	v_pk_mul_f32 v[48:49], v[48:49], v[108:109]
	v_pk_mul_f32 v[44:45], v[44:45], v[96:97]
	v_pk_mul_f32 v[40:41], v[40:41], v[100:101]
	v_pk_mul_f32 v[36:37], v[36:37], v[104:105]
	v_pk_mul_f32 v[46:47], v[46:47], v[98:99]
	v_pk_mul_f32 v[42:43], v[42:43], v[102:103]
	v_pk_mul_f32 v[38:39], v[38:39], v[106:107]
	v_pk_mul_f32 v[34:35], v[34:35], v[110:111]
	v_pk_mul_f32 v[32:33], v[32:33], v[108:109]
	v_pk_mul_f32 v[12:13], v[12:13], v[96:97]
	v_pk_mul_f32 v[8:9], v[8:9], v[100:101]
	v_pk_mul_f32 v[4:5], v[4:5], v[104:105]
	v_pk_mul_f32 v[14:15], v[14:15], v[98:99]
	v_pk_mul_f32 v[10:11], v[10:11], v[102:103]
	v_pk_mul_f32 v[6:7], v[6:7], v[106:107]
	v_pk_mul_f32 v[2:3], v[2:3], v[110:111]
	v_pk_mul_f32 v[0:1], v[0:1], v[108:109]

; #define LAS __attribute__((address_space(3)))
; __device__ __forceinline__ int lane_id() { return (int)__builtin_amdgcn_mbcnt_hi(~0u, __builtin_amdgcn_mbcnt_lo(~0u, 0u)); }
; __device__ __forceinline__ int v_rd_base(int lane) { return ((lane & 3) << 3) | (((lane >> 2) & 3) << 6) | (((lane >> 4) & 1) << 5) | (((lane >> 5) & 1) << 8); }
; #define DMA_V(t, vo) do { const char* vt_ = (const char*)(Vh + (size_t)(t) * KVBLK * LDK); \
;     _Pragma("unroll") for (int i_ = 0; i_ < 2; ++i_) \
;         __builtin_amdgcn_global_load_lds((const unsigned*)(vt_ + voffV[0] + i_ * 128), (LAS unsigned*)(lds + OFF_VR + (vo) + (wid * 2 + i_) * 1024), 16, 0, 0); } while (0)
; #define LBAR() asm volatile("s_waitcnt vmcnt(0) lgkmcnt(0)\n\ts_barrier" ::: "memory")
; template <int MODE, bool STORE = true> ...
;     ...
;     int tid = wv * 64 + lane_id(); asm volatile("" : "+v"(tid));
;     const int wid = __builtin_amdgcn_readfirstlane(tid >> 6), lane = tid & 63, r32 = lane & 31, hi = lane >> 5;
;     const int comp = MODE ? 0 : (wid >> 2), wq = MODE ? wid : (wid & 3);
;     LAS float* wsf = (LAS float*)(lds + OFF_WS) + wid * 64; LAS float* li_l = wsf; LAS float* al_l = wsf + 32;
;     float m_reg = -1e30f, l_reg = 0; f32x16 o[4] = {}; bf16x8 qr[ND];
;     const bf16_t* Qw = Qb + (size_t)(wq * 32 + r32) * LDQ + comp * 64 + hi * 8;
; #pragma unroll
;     for (int d0 = 0; d0 < ND; ++d0) qr[d0] = *(const bf16x8*)(Qw + d0 * 16);
;     unsigned voffV[2], voffK[2];
; #pragma unroll
;     for (int i = 0; i < 2; ++i) {
;         const int c = wid * 2 + i, ob = c * 1024 + lane * 16;
;         { const int sub = ob >> 9, within = ob & 511, kk = (sub >> 2) * 8 + (within >> 6), k = (kk & ~0xC) | ((kk & 4) << 1) | ((kk & 8) >> 1), col = (sub & 3) * 32 + ((within & 63) >> 1);
;           voffV[i] = (unsigned)(k * LDK + col) * 2u; }
;         { const int row = 4 * c + (lane >> 4), g = lane & 15; voffK[i] = (unsigned)(row * LDK + ((g ^ (row & 15)) * 8)) * 2u; }
;     }
;     const int vb0 = (int)(unsigned)(uintptr_t)lds + v_rd_base(lane);
;     ...
;     f32x16 pA0, pA1, pB0, pB1; float mnA, alA, alB; bf16x8 pa0, pa1, pa2, pa3; const int NT = seq / KVBLK;
;     const bool g2 = wid >= 4;
;     if (g2) __builtin_amdgcn_s_setprio(1);
;     int k_cur = 0, v_pp = SHM_V, v_p = 2 * SHM_V, v_c = 0;
;     DMA_K(0, 0); DMA_K(1, 1); DMA_V(0, 0); LBAR();
.LBB0_595:
	s_lshl_b32 s75, s0, 12
	s_add_u32 s1, s29, s75
	s_addc_u32 s4, s30, 0
	s_lshl_b32 s5, s49, 9
	s_add_u32 s64, s1, s5
	s_addc_u32 s65, s4, 0
	s_lshl_b32 s74, s0, 7
	v_and_b32_e32 v38, 63, v36
	s_add_u32 s72, s19, s74
	s_addc_u32 s73, s28, 0
	v_lshlrev_b32_e32 v43, 3, v38
	s_lshl_b32 s0, s16, 3
	v_lshrrev_b32_e32 v0, 2, v36
	v_bfe_u32 v41, v36, 2, 2
	s_and_b32 s83, s0, 0xffff0
	v_and_b32_e32 v42, 4, v0
	s_lshl_b32 s1, s16, 3
	v_and_b32_e32 v45, 24, v43
	s_and_b32 s92, s1, 8
	v_or3_b32 v0, v42, v41, s83
	v_and_or_b32 v1, v36, 32, v45
	v_lshrrev_b32_e32 v37, 4, v38
	v_or_b32_e32 v0, s92, v0
	v_or_b32_e32 v2, s0, v37
	v_lshlrev_b32_e32 v1, 1, v1
	v_lshl_or_b32 v180, v0, 12, v1
	v_bitop3_b32 v0, s0, v36, v37 bitop3:0x36
	v_bitop3_b32 v1, v2, v36, 4 bitop3:0x36
	v_lshlrev_b32_e32 v0, 4, v0
	v_lshlrev_b32_e32 v1, 4, v1
	s_lshl_b32 s80, s16, 11
	v_and_b32_e32 v39, 0xf0, v0
	v_or_b32_e32 v0, 4, v2
	v_and_b32_e32 v40, 0xf0, v1
	s_add_i32 s84, s80, 0
	v_lshrrev_b32_e32 v44, 3, v38
	v_lshl_or_b32 v184, v0, 12, v40
	s_add_i32 s69, s84, 0xc000
	v_or_b32_e32 v0, s0, v44
	v_lshl_or_b32 v182, v2, 12, v39
	s_mov_b32 m0, s69
	s_add_i32 s20, s84, 0xc400
	v_lshrrev_b32_e32 v1, 1, v0
	global_load_lds_dwordx4 v182, s[64:65]
	s_mov_b32 m0, s20
	v_xor_b32_e32 v1, v1, v36
	s_lshl_b32 s93, s16, 10
	global_load_lds_dwordx4 v184, s[64:65]
	v_lshlrev_b32_e32 v1, 4, v1
	s_add_i32 m0, s35, s93
	v_and_b32_e32 v46, 0x70, v1
	s_add_u32 s0, s64, 0x40000
	v_lshl_or_b32 v176, v0, 7, v46
	s_addc_u32 s1, s65, 0
	s_add_i32 s89, s84, 0x10000
	global_load_lds_dwordx4 v176, s[72:73]
	s_mov_b32 m0, s89
	s_add_i32 s90, s84, 0x10400
	global_load_lds_dwordx4 v182, s[0:1]
	s_mov_b32 m0, s90
	s_add_i32 s85, s93, 0
	v_lshl_add_u64 v[32:33], s[72:73], 0, v[176:177]
	global_load_lds_dwordx4 v184, s[0:1]
	s_mov_b64 s[0:1], 0x2000
	s_add_i32 s91, s85, 0x16000
	v_mov_b32_e32 v181, v177
	v_lshl_add_u64 v[0:1], v[32:33], 0, s[0:1]
	s_mov_b32 m0, s91
	v_lshl_add_u64 v[34:35], s[64:65], 0, v[180:181]
	global_load_lds_dwordx4 v[0:1], off
	v_lshl_add_u64 v[0:1], v[34:35], 0, s[22:23]
	s_mov_b32 m0, s84
	v_lshlrev_b32_e32 v47, 8, v254
	global_load_lds_dwordx4 v[0:1], off
	v_lshl_add_u64 v[0:1], v[34:35], 0, s[24:25]
	s_add_i32 m0, s84, 0x400
	s_movk_i32 s0, 0xf0
	global_load_lds_dwordx4 v[0:1], off
	v_lshlrev_b32_e32 v0, 4, v254
	v_add_u32_e32 v57, 0, v47
	v_bitop3_b32 v204, v178, v0, s0 bitop3:0x78
	s_waitcnt vmcnt(0) lgkmcnt(0)
	s_barrier
; #define LAS __attribute__((address_space(3)))
; template <int MODE> __device__ __forceinline__ void partialSM(f32x16& p0, f32x16& p1, float& m_reg, float& mn, float& alpha) {
;     float pmax = p0[0];
; #pragma unroll
;     for (int r = 1; r < 16; ++r) pmax = fmaxf(pmax, p0[r]);
; #pragma unroll
;     for (int r = 0; r < 16; ++r) pmax = fmaxf(pmax, p1[r]);
;     { auto rr = __builtin_amdgcn_permlane32_swap(__float_as_uint(pmax), __float_as_uint(pmax), false, false);
;       pmax = fmaxf(__uint_as_float(rr[0]), __uint_as_float(rr[1])); }
;     if (__builtin_expect(__all(pmax - m_reg <= Cst<MODE>::THRS), 1)) { mn = m_reg; alpha = 1.f; }
; template <int MODE> __device__ __forceinline__ void qkt(f32x16& p0, f32x16& p1, const LAS unsigned char* Kt, const LAS unsigned char* Krt, const bf16x8* qr, int r32, int hi, int comp) {
;     p0 = f32x16{}; p1 = f32x16{};
;     constexpr int NDN = MODE ? 8 : 4;
; #pragma unroll
;     for (int d0 = 0; d0 < NDN; ++d0) { const int cb = ((MODE ? 0 : comp * 64) + d0 * 16 + hi * 8) * 2;
;         const bf16x8 b0 = *(const LAS bf16x8*)(Kt + KSWZ(r32, cb));
;         const bf16x8 b1 = *(const LAS bf16x8*)(Kt + KSWZ(32 + r32, cb));
;         p0 = __builtin_amdgcn_mfma_f32_32x32x16_bf16(b0, qr[d0], p0, 0, 0, 0);
;         p1 = __builtin_amdgcn_mfma_f32_32x32x16_bf16(b1, qr[d0], p1, 0, 0, 0); }
;     if constexpr (MODE == 1) {
; #pragma unroll
;         for (int d0 = 0; d0 < 4; ++d0) { const int cb = (d0 * 16 + hi * 8) * 2;
;             const bf16x8 b0 = *(const LAS bf16x8*)(Krt + KRSWZ(r32, cb));
;             const bf16x8 b1 = *(const LAS bf16x8*)(Krt + KRSWZ(32 + r32, cb));
;             p0 = __builtin_amdgcn_mfma_f32_32x32x16_bf16(b0, qr[8 + d0], p0, 0, 0, 0);
;             p1 = __builtin_amdgcn_mfma_f32_32x32x16_bf16(b1, qr[8 + d0], p1, 0, 0, 0); }
;     }
; }
	v_add_u32_e32 v205, v57, v204
	v_and_b32_e32 v56, 0xf0, v0
	ds_read_b128 v[0:3], v205 offset:49152
	ds_read_b128 v[4:7], v205 offset:57344
	s_waitcnt vmcnt(0) lgkmcnt(0)
	v_mfma_f32_32x32x16_bf16 v[16:31], v[0:3], v[172:175], 0
	v_bitop3_b32 v206, v178, v56, 32 bitop3:0x36
	v_add_u32_e32 v207, v57, v206
	ds_read_b128 v[48:51], v207 offset:49152
	ds_read_b128 v[52:55], v207 offset:57344
	v_bitop3_b32 v208, v178, v56, 64 bitop3:0x36
	v_add_u32_e32 v209, v57, v208
	v_bitop3_b32 v210, v178, v56, s76 bitop3:0x36
	v_add_u32_e32 v211, v57, v210
	v_mfma_f32_32x32x16_bf16 v[0:15], v[4:7], v[172:175], 0
	s_movk_i32 s0, 0x80
	v_bitop3_b32 v212, v178, v56, s0 bitop3:0x36
	v_add_u32_e32 v213, v57, v212
	s_movk_i32 s0, 0xa0
	v_bitop3_b32 v214, v178, v56, s0 bitop3:0x36
	v_add_u32_e32 v215, v57, v214
	v_bitop3_b32 v216, v178, v56, s77 bitop3:0x36
	s_waitcnt lgkmcnt(1)
	v_mfma_f32_32x32x16_bf16 v[16:31], v[48:51], v[168:171], v[16:31]
	v_add_u32_e32 v217, v57, v216
	s_movk_i32 s0, 0xe0
	v_bitop3_b32 v218, v178, v56, s0 bitop3:0x36
	v_add_u32_e32 v219, v57, v218
	s_movk_i32 s0, 0x70
	s_mov_b64 s[4:5], -1
	s_waitcnt lgkmcnt(0)
	v_mfma_f32_32x32x16_bf16 v[0:15], v[52:55], v[168:171], v[0:15]
	ds_read_b128 v[48:51], v209 offset:49152
	ds_read_b128 v[52:55], v209 offset:57344
	s_waitcnt lgkmcnt(1)
	v_mfma_f32_32x32x16_bf16 v[16:31], v[48:51], v[164:167], v[16:31]
	s_waitcnt lgkmcnt(0)
	v_mfma_f32_32x32x16_bf16 v[0:15], v[52:55], v[164:167], v[0:15]
	ds_read_b128 v[48:51], v211 offset:49152
	ds_read_b128 v[52:55], v211 offset:57344
	s_waitcnt lgkmcnt(1)
	v_mfma_f32_32x32x16_bf16 v[16:31], v[48:51], v[160:163], v[16:31]
	s_waitcnt lgkmcnt(0)
	v_mfma_f32_32x32x16_bf16 v[0:15], v[52:55], v[160:163], v[0:15]
	ds_read_b128 v[48:51], v213 offset:49152
	ds_read_b128 v[52:55], v213 offset:57344
	s_waitcnt lgkmcnt(1)
	v_mfma_f32_32x32x16_bf16 v[16:31], v[48:51], v[156:159], v[16:31]
	s_waitcnt lgkmcnt(0)
	v_mfma_f32_32x32x16_bf16 v[0:15], v[52:55], v[156:159], v[0:15]
	ds_read_b128 v[48:51], v215 offset:49152
	ds_read_b128 v[52:55], v215 offset:57344
	s_waitcnt lgkmcnt(1)
	v_mfma_f32_32x32x16_bf16 v[16:31], v[48:51], v[152:155], v[16:31]
	s_waitcnt lgkmcnt(0)
	v_mfma_f32_32x32x16_bf16 v[0:15], v[52:55], v[152:155], v[0:15]
	ds_read_b128 v[48:51], v217 offset:49152
	ds_read_b128 v[52:55], v217 offset:57344
	s_waitcnt lgkmcnt(1)
	v_mfma_f32_32x32x16_bf16 v[16:31], v[48:51], v[148:151], v[16:31]
	s_waitcnt lgkmcnt(0)
	v_mfma_f32_32x32x16_bf16 v[0:15], v[52:55], v[148:151], v[0:15]
	ds_read_b128 v[48:51], v219 offset:49152
	ds_read_b128 v[52:55], v219 offset:57344
	s_waitcnt lgkmcnt(1)
	v_mfma_f32_32x32x16_bf16 v[16:31], v[48:51], v[144:147], v[16:31]
	v_lshlrev_b32_e32 v48, 7, v254
	v_lshlrev_b32_e32 v49, 3, v254
	v_add_u32_e32 v59, s35, v48
	v_bitop3_b32 v220, v178, v49, s0 bitop3:0x78
	v_add_u32_e32 v221, v59, v220
	v_and_b32_e32 v58, 0x70, v49
	v_bitop3_b32 v222, v178, v58, 32 bitop3:0x36
	s_waitcnt lgkmcnt(0)
	v_mfma_f32_32x32x16_bf16 v[0:15], v[52:55], v[144:147], v[0:15]
	ds_read_b128 v[50:53], v221
	ds_read_b128 v[54:57], v221 offset:4096
	v_add_u32_e32 v223, v59, v222
	v_bitop3_b32 v224, v178, v58, 64 bitop3:0x36
	v_add_u32_e32 v225, v59, v224
	v_bitop3_b32 v226, v178, v58, s76 bitop3:0x36
	v_add_u32_e32 v227, v59, v226
	s_waitcnt lgkmcnt(1)
	v_mfma_f32_32x32x16_bf16 v[16:31], v[50:53], v[140:143], v[16:31]
	s_waitcnt lgkmcnt(0)
	v_mfma_f32_32x32x16_bf16 v[0:15], v[54:57], v[140:143], v[0:15]
	ds_read_b128 v[50:53], v223
	ds_read_b128 v[54:57], v223 offset:4096
	s_waitcnt lgkmcnt(1)
	v_mfma_f32_32x32x16_bf16 v[16:31], v[50:53], v[136:139], v[16:31]
	s_waitcnt lgkmcnt(0)
	v_mfma_f32_32x32x16_bf16 v[0:15], v[54:57], v[136:139], v[0:15]
	ds_read_b128 v[50:53], v225
	ds_read_b128 v[54:57], v225 offset:4096
	s_waitcnt lgkmcnt(1)
	v_mfma_f32_32x32x16_bf16 v[16:31], v[50:53], v[132:135], v[16:31]
	s_waitcnt lgkmcnt(0)
	v_mfma_f32_32x32x16_bf16 v[0:15], v[54:57], v[132:135], v[0:15]
	ds_read_b128 v[50:53], v227
	ds_read_b128 v[54:57], v227 offset:4096
	s_waitcnt lgkmcnt(1)
	v_mfma_f32_32x32x16_bf16 v[16:31], v[50:53], v[128:131], v[16:31]
	s_waitcnt lgkmcnt(0)
	v_mfma_f32_32x32x16_bf16 v[0:15], v[54:57], v[128:131], v[0:15]
	s_nop 9
	v_max_f32_e32 v49, v16, v17
	v_max3_f32 v49, v49, v18, v19
	v_max3_f32 v49, v49, v20, v21
	v_max3_f32 v49, v49, v22, v23
	v_max3_f32 v49, v49, v24, v25
	v_max3_f32 v49, v49, v26, v27
	v_max3_f32 v49, v49, v28, v29
	v_max3_f32 v49, v49, v30, v31
	v_max3_f32 v49, v49, v0, v1
	v_max3_f32 v49, v49, v2, v3
	v_max3_f32 v49, v49, v4, v5
	v_max3_f32 v49, v49, v6, v7
	v_max3_f32 v49, v49, v8, v9
	v_max3_f32 v49, v49, v10, v11
	v_max3_f32 v49, v49, v12, v13
	v_max3_f32 v49, v49, v14, v15
	v_mov_b32_e32 v50, v49
	s_nop 1
	v_permlane32_swap_b32_e32 v49, v50
	v_max_f32_e32 v50, v50, v50
	v_max_f32_e32 v49, v49, v49
	v_max_f32_e32 v49, v49, v50
	v_add_f32_e32 v50, 0x7149f2ca, v49
	v_cmp_ge_f32_e32 vcc, s78, v50
	s_cmp_eq_u64 vcc, exec
	s_cselect_b64 s[0:1], -1, 0
	s_and_b64 vcc, exec, s[66:67]
	s_cbranch_vccz .LBB0_597
	s_waitcnt vmcnt(0) lgkmcnt(0)
	s_barrier
	s_mov_b64 s[4:5], 0

; #define SBAR() __builtin_amdgcn_sched_barrier(0)
; #define LW(n) asm volatile("s_waitcnt lgkmcnt(" #n ")" ::: "memory")
; template <int MODE, bool PF> __device__ __forceinline__ void pv_partial(f32x16* o, int vb, bf16x8 pa0, bf16x8 pa1, bf16x8 pa2, bf16x8 pa3, f32x16& p0, f32x16& p1, float& m_reg, float& alpha) {
;     VFrag fa, fb;
;     v_frag_read<0>(fa, vb);
;     if constexpr (PF) { v_frag_read<1>(fb, vb); LW(8); } else LW(0);
;     SBAR();
;     pv_mma(o[0], fa, pa0, pa1, pa2, pa3);
;     float pm0 = p0[0];
; #pragma unroll
;     for (int r = 1; r < 16; ++r) pm0 = fmaxf(pm0, p0[r]);
;     if constexpr (PF) { v_frag_read<2>(fa, vb); LW(8); } else { v_frag_read<1>(fb, vb); LW(0); }
;     SBAR();
;     pv_mma(o[1], fb, pa0, pa1, pa2, pa3);
;     float pmax = pm0;
; #pragma unroll
;     for (int r = 0; r < 16; ++r) pmax = fmaxf(pmax, p1[r]);
;     { auto rr = __builtin_amdgcn_permlane32_swap(__float_as_uint(pmax), __float_as_uint(pmax), false, false);
;       pmax = fmaxf(__uint_as_float(rr[0]), __uint_as_float(rr[1])); }
;     const float mn = (pmax - m_reg > Cst<MODE>::THRS) ? fmaxf(m_reg, pmax) : m_reg;
;     alpha = __builtin_amdgcn_exp2f(m_reg - mn); m_reg = mn;
;     const f32x16 mnv = {mn, mn, mn, mn, mn, mn, mn, mn, mn, mn, mn, mn, mn, mn, mn, mn};
;     if constexpr (PF) { v_frag_read<3>(fb, vb); LW(8); } else { v_frag_read<2>(fa, vb); LW(0); }
;     SBAR();
;     pv_mma(o[2], fa, pa0, pa1, pa2, pa3);
;     p0 = p0 - mnv; p1 = p1 - mnv;
; #pragma unroll
;     for (int r = 0; r < 8; ++r) p0[r] = __builtin_amdgcn_exp2f(p0[r]);
;     if constexpr (PF) { LW(0); } else { v_frag_read<3>(fb, vb); LW(0); }
;     SBAR();
;     pv_mma(o[3], fb, pa0, pa1, pa2, pa3);
; #pragma unroll
;     for (int r = 8; r < 16; ++r) p0[r] = __builtin_amdgcn_exp2f(p0[r]);
;     asm volatile("" : "+v"(p0), "+v"(p1));
; }
.LBB0_604:
	v_add_u32_e32 v197, s93, v203
	ds_read_b64_tr_b16 v[64:65], v197 offset:0
	ds_read_b64_tr_b16 v[66:67], v197 offset:0x800
	ds_read_b64_tr_b16 v[68:69], v197 offset:0x1000
	ds_read_b64_tr_b16 v[70:71], v197 offset:0x1800
	ds_read_b64_tr_b16 v[88:89], v197 offset:0x2000
	ds_read_b64_tr_b16 v[90:91], v197 offset:0x2800
	ds_read_b64_tr_b16 v[92:93], v197 offset:0x3000
	ds_read_b64_tr_b16 v[94:95], v197 offset:0x3800
	s_waitcnt lgkmcnt(0)
	s_nop 0
	v_mfma_f32_32x32x16_bf16 v[0:15], v[84:87], v[64:67], v[0:15]
	v_max_f32_e32 v64, v112, v113
	v_max3_f32 v64, v64, v114, v115
	v_max3_f32 v64, v64, v116, v117
	v_max3_f32 v64, v64, v118, v119
	v_max3_f32 v64, v64, v120, v121
	v_mfma_f32_32x32x16_bf16 v[0:15], v[72:75], v[68:71], v[0:15]
	v_max3_f32 v64, v64, v122, v123
	v_max3_f32 v64, v64, v124, v125
	v_max3_f32 v198, v64, v126, v127
	ds_read_b64_tr_b16 v[64:65], v197 offset:0x200
	ds_read_b64_tr_b16 v[66:67], v197 offset:0xa00
	ds_read_b64_tr_b16 v[68:69], v197 offset:0x1200
	ds_read_b64_tr_b16 v[70:71], v197 offset:0x1a00
	v_mfma_f32_32x32x16_bf16 v[0:15], v[76:79], v[88:91], v[0:15]
	ds_read_b64_tr_b16 v[88:89], v197 offset:0x2200
	ds_read_b64_tr_b16 v[90:91], v197 offset:0x2a00
	v_mfma_f32_32x32x16_bf16 v[0:15], v[80:83], v[92:95], v[0:15]
	ds_read_b64_tr_b16 v[92:93], v197 offset:0x3200
	ds_read_b64_tr_b16 v[94:95], v197 offset:0x3a00
	s_waitcnt lgkmcnt(0)
	v_mfma_f32_32x32x16_bf16 v[48:63], v[84:87], v[64:67], v[48:63]
	v_max3_f32 v64, v198, v96, v97
	v_max3_f32 v64, v64, v98, v99
	v_max3_f32 v64, v64, v100, v101
	v_max3_f32 v64, v64, v102, v103
	v_max3_f32 v64, v64, v104, v105
	v_max3_f32 v64, v64, v106, v107
	v_max3_f32 v64, v64, v108, v109
	v_mfma_f32_32x32x16_bf16 v[48:63], v[72:75], v[68:71], v[48:63]
	v_max3_f32 v64, v64, v110, v111
	v_mov_b32_e32 v65, v64
	s_nop 1
	v_permlane32_swap_b32_e32 v64, v65
	v_max_f32_e32 v65, v65, v65
	v_max_f32_e32 v64, v64, v64
	v_max_f32_e32 v64, v64, v65
	v_mfma_f32_32x32x16_bf16 v[48:63], v[76:79], v[88:91], v[48:63]
	v_sub_f32_e32 v65, v64, v243
	v_cmp_lt_f32_e32 vcc, s78, v65
	v_max_f32_e32 v65, v243, v243
	v_max_f32_e32 v64, v65, v64
	v_cndmask_b32_e32 v244, v243, v64, vcc
	v_sub_f32_e32 v64, v243, v244
	v_exp_f32_e32 v246, v64
	ds_read_b64_tr_b16 v[64:65], v197 offset:0x400
	ds_read_b64_tr_b16 v[66:67], v197 offset:0xc00
	ds_read_b64_tr_b16 v[68:69], v197 offset:0x1400
	v_mfma_f32_32x32x16_bf16 v[48:63], v[80:83], v[92:95], v[48:63]
	ds_read_b64_tr_b16 v[70:71], v197 offset:0x1c00
	ds_read_b64_tr_b16 v[88:89], v197 offset:0x2400
	ds_read_b64_tr_b16 v[90:91], v197 offset:0x2c00
	ds_read_b64_tr_b16 v[92:93], v197 offset:0x3400
	ds_read_b64_tr_b16 v[94:95], v197 offset:0x3c00
	s_waitcnt lgkmcnt(0)
	v_mfma_f32_32x32x16_bf16 v[32:47], v[84:87], v[64:67], v[32:47]
	v_sub_f32_e32 v65, v113, v244
	v_sub_f32_e32 v64, v112, v244
	v_sub_f32_e32 v113, v97, v244
	v_sub_f32_e32 v112, v96, v244
	v_sub_f32_e32 v67, v115, v244
	v_sub_f32_e32 v66, v114, v244
	v_sub_f32_e32 v115, v99, v244
	v_mfma_f32_32x32x16_bf16 v[32:47], v[72:75], v[68:71], v[32:47]
	v_sub_f32_e32 v114, v98, v244
	v_sub_f32_e32 v71, v119, v244
	v_sub_f32_e32 v70, v118, v244
	v_sub_f32_e32 v69, v117, v244
	v_sub_f32_e32 v68, v116, v244
	v_sub_f32_e32 v117, v101, v244
	v_sub_f32_e32 v116, v100, v244
	v_mfma_f32_32x32x16_bf16 v[32:47], v[76:79], v[88:91], v[32:47]
	ds_read_b64_tr_b16 v[88:89], v197 offset:0x600
	ds_read_b64_tr_b16 v[90:91], v197 offset:0xe00
	v_sub_f32_e32 v119, v103, v244
	v_sub_f32_e32 v118, v102, v244
	v_exp_f32_e32 v64, v64
	v_exp_f32_e32 v65, v65
	v_exp_f32_e32 v66, v66
	v_mfma_f32_32x32x16_bf16 v[32:47], v[80:83], v[92:95], v[32:47]
	ds_read_b64_tr_b16 v[92:93], v197 offset:0x1600
	ds_read_b64_tr_b16 v[94:95], v197 offset:0x1e00
	ds_read_b64_tr_b16 v[96:97], v197 offset:0x2600
	ds_read_b64_tr_b16 v[98:99], v197 offset:0x2e00
	ds_read_b64_tr_b16 v[100:101], v197 offset:0x3600
	v_exp_f32_e32 v67, v67
	v_exp_f32_e32 v68, v68
	v_exp_f32_e32 v69, v69
	v_exp_f32_e32 v70, v70
	v_exp_f32_e32 v71, v71
	ds_read_b64_tr_b16 v[102:103], v197 offset:0x3e00
	s_waitcnt lgkmcnt(0)
	v_sub_f32_e32 v198, v127, v244
	v_sub_f32_e32 v199, v126, v244
	v_sub_f32_e32 v200, v125, v244
	v_sub_f32_e32 v201, v124, v244
	v_sub_f32_e32 v243, v123, v244
	v_sub_f32_e32 v247, v122, v244
	v_sub_f32_e32 v248, v121, v244
	v_sub_f32_e32 v249, v120, v244
	v_sub_f32_e32 v127, v111, v244
	v_sub_f32_e32 v126, v110, v244
	v_sub_f32_e32 v125, v109, v244
	v_sub_f32_e32 v124, v108, v244
	v_sub_f32_e32 v123, v107, v244
	v_sub_f32_e32 v122, v106, v244
	v_sub_f32_e32 v121, v105, v244
	v_sub_f32_e32 v120, v104, v244
	v_mfma_f32_32x32x16_bf16 v[16:31], v[84:87], v[88:91], v[16:31]
	v_cmp_gt_f32_e32 vcc, 1.0, v246
	v_mfma_f32_32x32x16_bf16 v[16:31], v[72:75], v[92:95], v[16:31]
	v_exp_f32_e32 v72, v249
	v_exp_f32_e32 v73, v248
	v_exp_f32_e32 v74, v247
	v_exp_f32_e32 v75, v243
	v_mfma_f32_32x32x16_bf16 v[16:31], v[76:79], v[96:99], v[16:31]
	v_exp_f32_e32 v76, v201
	v_exp_f32_e32 v77, v200
	v_exp_f32_e32 v78, v199
	v_exp_f32_e32 v79, v198
	v_mfma_f32_32x32x16_bf16 v[16:31], v[80:83], v[100:103], v[16:31]
	s_cbranch_vccz .LBB0_608
	s_and_saveexec_b64 s[74:75], s[0:1]
	ds_write_b32 v179, v246 offset:128
	s_or_b64 exec, exec, s[74:75]
	s_waitcnt lgkmcnt(0)
	v_add_u32_e32 v92, s81, v178
	ds_read_b128 v[80:83], v92 offset:224
	ds_read_b128 v[84:87], v92 offset:192
	ds_read_b128 v[88:91], v92 offset:160
	ds_read_b128 v[92:95], v92 offset:128
	s_waitcnt lgkmcnt(0)
	v_pk_mul_f32 v[12:13], v[12:13], v[80:81]
	v_pk_mul_f32 v[8:9], v[8:9], v[84:85]
	v_pk_mul_f32 v[4:5], v[4:5], v[88:89]
	v_pk_mul_f32 v[14:15], v[14:15], v[82:83]
	v_pk_mul_f32 v[10:11], v[10:11], v[86:87]
	v_pk_mul_f32 v[6:7], v[6:7], v[90:91]
	v_pk_mul_f32 v[2:3], v[2:3], v[94:95]
	v_pk_mul_f32 v[0:1], v[0:1], v[92:93]
	v_pk_mul_f32 v[60:61], v[60:61], v[80:81]
	v_pk_mul_f32 v[56:57], v[56:57], v[84:85]
	v_pk_mul_f32 v[52:53], v[52:53], v[88:89]
	v_pk_mul_f32 v[62:63], v[62:63], v[82:83]
	v_pk_mul_f32 v[58:59], v[58:59], v[86:87]
	v_pk_mul_f32 v[54:55], v[54:55], v[90:91]
	v_pk_mul_f32 v[50:51], v[50:51], v[94:95]
	v_pk_mul_f32 v[48:49], v[48:49], v[92:93]
	v_pk_mul_f32 v[44:45], v[44:45], v[80:81]
	v_pk_mul_f32 v[40:41], v[40:41], v[84:85]
	v_pk_mul_f32 v[36:37], v[36:37], v[88:89]
	v_pk_mul_f32 v[46:47], v[46:47], v[82:83]
	v_pk_mul_f32 v[42:43], v[42:43], v[86:87]
	v_pk_mul_f32 v[38:39], v[38:39], v[90:91]
	v_pk_mul_f32 v[34:35], v[34:35], v[94:95]
	v_pk_mul_f32 v[32:33], v[32:33], v[92:93]
	v_pk_mul_f32 v[28:29], v[28:29], v[80:81]
	v_pk_mul_f32 v[24:25], v[24:25], v[84:85]
	v_pk_mul_f32 v[20:21], v[20:21], v[88:89]
	v_pk_mul_f32 v[30:31], v[30:31], v[82:83]
	v_pk_mul_f32 v[26:27], v[26:27], v[86:87]
	v_pk_mul_f32 v[22:23], v[22:23], v[90:91]
	v_pk_mul_f32 v[18:19], v[18:19], v[94:95]
	v_pk_mul_f32 v[16:17], v[16:17], v[92:93]

; #define SBAR() __builtin_amdgcn_sched_barrier(0)
; #define LW(n) asm volatile("s_waitcnt lgkmcnt(" #n ")" ::: "memory")
; template <int MODE, bool PF> __device__ __forceinline__ void pv_partial(f32x16* o, int vb, bf16x8 pa0, bf16x8 pa1, bf16x8 pa2, bf16x8 pa3, f32x16& p0, f32x16& p1, float& m_reg, float& alpha) {
;     VFrag fa, fb;
;     v_frag_read<0>(fa, vb);
;     if constexpr (PF) { v_frag_read<1>(fb, vb); LW(8); } else LW(0);
;     SBAR();
;     pv_mma(o[0], fa, pa0, pa1, pa2, pa3);
;     float pm0 = p0[0];
; #pragma unroll
;     for (int r = 1; r < 16; ++r) pm0 = fmaxf(pm0, p0[r]);
;     if constexpr (PF) { v_frag_read<2>(fa, vb); LW(8); } else { v_frag_read<1>(fb, vb); LW(0); }
;     SBAR();
;     pv_mma(o[1], fb, pa0, pa1, pa2, pa3);
;     float pmax = pm0;
; #pragma unroll
;     for (int r = 0; r < 16; ++r) pmax = fmaxf(pmax, p1[r]);
;     { auto rr = __builtin_amdgcn_permlane32_swap(__float_as_uint(pmax), __float_as_uint(pmax), false, false);
;       pmax = fmaxf(__uint_as_float(rr[0]), __uint_as_float(rr[1])); }
;     const float mn = (pmax - m_reg > Cst<MODE>::THRS) ? fmaxf(m_reg, pmax) : m_reg;
;     alpha = __builtin_amdgcn_exp2f(m_reg - mn); m_reg = mn;
;     const f32x16 mnv = {mn, mn, mn, mn, mn, mn, mn, mn, mn, mn, mn, mn, mn, mn, mn, mn};
;     if constexpr (PF) { v_frag_read<3>(fb, vb); LW(8); } else { v_frag_read<2>(fa, vb); LW(0); }
;     SBAR();
;     pv_mma(o[2], fa, pa0, pa1, pa2, pa3);
;     p0 = p0 - mnv; p1 = p1 - mnv;
; #pragma unroll
;     for (int r = 0; r < 8; ++r) p0[r] = __builtin_amdgcn_exp2f(p0[r]);
;     if constexpr (PF) { LW(0); } else { v_frag_read<3>(fb, vb); LW(0); }
;     SBAR();
;     pv_mma(o[3], fb, pa0, pa1, pa2, pa3);
; #pragma unroll
;     for (int r = 8; r < 16; ++r) p0[r] = __builtin_amdgcn_exp2f(p0[r]);
;     asm volatile("" : "+v"(p0), "+v"(p1));
; }
.LBB0_616:
	s_nop 0
	v_add_u32_e32 v126, s83, v203
	ds_read_b64_tr_b16 v[64:65], v126 offset:0
	ds_read_b64_tr_b16 v[66:67], v126 offset:0x800
	ds_read_b64_tr_b16 v[68:69], v126 offset:0x1000
	ds_read_b64_tr_b16 v[70:71], v126 offset:0x1800
	ds_read_b64_tr_b16 v[122:123], v126 offset:0x2000
	ds_read_b64_tr_b16 v[124:125], v126 offset:0x2800
	ds_read_b64_tr_b16 v[198:199], v126 offset:0x3000
	ds_read_b64_tr_b16 v[200:201], v126 offset:0x3800
	s_waitcnt lgkmcnt(0)
	s_nop 0
	v_mfma_f32_32x32x16_bf16 v[0:15], v[116:119], v[64:67], v[0:15]
	v_max_f32_e32 v64, v96, v97
	v_max3_f32 v64, v64, v98, v99
	v_max3_f32 v64, v64, v100, v101
	v_max3_f32 v64, v64, v102, v103
	v_max3_f32 v64, v64, v104, v105
	v_mfma_f32_32x32x16_bf16 v[0:15], v[72:75], v[68:71], v[0:15]
	v_max3_f32 v64, v64, v106, v107
	v_max3_f32 v64, v64, v108, v109
	v_max3_f32 v127, v64, v110, v111
	ds_read_b64_tr_b16 v[64:65], v126 offset:0x200
	ds_read_b64_tr_b16 v[66:67], v126 offset:0xa00
	ds_read_b64_tr_b16 v[68:69], v126 offset:0x1200
	ds_read_b64_tr_b16 v[70:71], v126 offset:0x1a00
	v_mfma_f32_32x32x16_bf16 v[0:15], v[76:79], v[122:125], v[0:15]
	ds_read_b64_tr_b16 v[122:123], v126 offset:0x2200
	ds_read_b64_tr_b16 v[124:125], v126 offset:0x2a00
	v_mfma_f32_32x32x16_bf16 v[0:15], v[112:115], v[198:201], v[0:15]
	ds_read_b64_tr_b16 v[198:199], v126 offset:0x3200
	ds_read_b64_tr_b16 v[200:201], v126 offset:0x3a00
	s_waitcnt lgkmcnt(0)
	v_mfma_f32_32x32x16_bf16 v[48:63], v[116:119], v[64:67], v[48:63]
	v_max3_f32 v64, v127, v80, v81
	v_max3_f32 v64, v64, v82, v83
	v_max3_f32 v64, v64, v84, v85
	v_max3_f32 v64, v64, v86, v87
	v_max3_f32 v64, v64, v88, v89
	v_max3_f32 v64, v64, v90, v91
	v_max3_f32 v64, v64, v92, v93
	v_mfma_f32_32x32x16_bf16 v[48:63], v[72:75], v[68:71], v[48:63]
	v_max3_f32 v64, v64, v94, v95
	v_mov_b32_e32 v65, v64
	s_nop 1
	v_permlane32_swap_b32_e32 v64, v65
	v_max_f32_e32 v65, v65, v65
	v_max_f32_e32 v64, v64, v64
	v_max_f32_e32 v64, v64, v65
	v_mfma_f32_32x32x16_bf16 v[48:63], v[76:79], v[122:125], v[48:63]
	v_sub_f32_e32 v65, v64, v244
	v_cmp_lt_f32_e32 vcc, s78, v65
	v_max_f32_e32 v65, v244, v244
	v_max_f32_e32 v64, v65, v64
	v_cndmask_b32_e32 v243, v244, v64, vcc
	v_sub_f32_e32 v64, v244, v243
	v_exp_f32_e32 v244, v64
	ds_read_b64_tr_b16 v[64:65], v126 offset:0x400
	ds_read_b64_tr_b16 v[66:67], v126 offset:0xc00
	ds_read_b64_tr_b16 v[68:69], v126 offset:0x1400
	v_mfma_f32_32x32x16_bf16 v[48:63], v[112:115], v[198:201], v[48:63]
	ds_read_b64_tr_b16 v[70:71], v126 offset:0x1c00
	ds_read_b64_tr_b16 v[122:123], v126 offset:0x2400
	ds_read_b64_tr_b16 v[124:125], v126 offset:0x2c00
	ds_read_b64_tr_b16 v[198:199], v126 offset:0x3400
	ds_read_b64_tr_b16 v[200:201], v126 offset:0x3c00
	s_waitcnt lgkmcnt(0)
	v_mfma_f32_32x32x16_bf16 v[32:47], v[116:119], v[64:67], v[32:47]
	v_sub_f32_e32 v65, v97, v243
	v_sub_f32_e32 v64, v96, v243
	ds_read_b64_tr_b16 v[96:97], v126 offset:0x600
	v_sub_f32_e32 v67, v99, v243
	v_sub_f32_e32 v66, v98, v243
	ds_read_b64_tr_b16 v[98:99], v126 offset:0xe00
	v_sub_f32_e32 v127, v107, v243
	v_mfma_f32_32x32x16_bf16 v[32:47], v[72:75], v[68:71], v[32:47]
	v_sub_f32_e32 v69, v101, v243
	v_sub_f32_e32 v68, v100, v243
	ds_read_b64_tr_b16 v[100:101], v126 offset:0x1600
	v_sub_f32_e32 v71, v103, v243
	v_sub_f32_e32 v70, v102, v243
	ds_read_b64_tr_b16 v[102:103], v126 offset:0x1e00
	v_exp_f32_e32 v64, v64
	v_mfma_f32_32x32x16_bf16 v[32:47], v[76:79], v[122:125], v[32:47]
	v_sub_f32_e32 v124, v109, v243
	v_sub_f32_e32 v125, v108, v243
	v_sub_f32_e32 v122, v111, v243
	v_sub_f32_e32 v123, v110, v243
	v_exp_f32_e32 v65, v65
	v_exp_f32_e32 v66, v66
	v_exp_f32_e32 v67, v67
	v_mfma_f32_32x32x16_bf16 v[32:47], v[112:115], v[198:201], v[32:47]
	v_sub_f32_e32 v199, v105, v243
	v_sub_f32_e32 v200, v104, v243
	ds_read_b64_tr_b16 v[104:105], v126 offset:0x2600
	v_sub_f32_e32 v198, v106, v243
	ds_read_b64_tr_b16 v[106:107], v126 offset:0x2e00
	ds_read_b64_tr_b16 v[108:109], v126 offset:0x3600
	v_exp_f32_e32 v68, v68
	v_exp_f32_e32 v69, v69
	v_exp_f32_e32 v70, v70
	v_exp_f32_e32 v71, v71
	ds_read_b64_tr_b16 v[110:111], v126 offset:0x3e00
	s_waitcnt lgkmcnt(0)
	v_sub_f32_e32 v95, v95, v243
	v_sub_f32_e32 v94, v94, v243
	v_sub_f32_e32 v93, v93, v243
	v_sub_f32_e32 v92, v92, v243
	v_sub_f32_e32 v91, v91, v243
	v_sub_f32_e32 v90, v90, v243
	v_sub_f32_e32 v89, v89, v243
	v_sub_f32_e32 v88, v88, v243
	v_sub_f32_e32 v87, v87, v243
	v_sub_f32_e32 v86, v86, v243
	v_sub_f32_e32 v85, v85, v243
	v_sub_f32_e32 v84, v84, v243
	v_sub_f32_e32 v83, v83, v243
	v_sub_f32_e32 v82, v82, v243
	v_sub_f32_e32 v81, v81, v243
	v_sub_f32_e32 v80, v80, v243
	v_mfma_f32_32x32x16_bf16 v[16:31], v[116:119], v[96:99], v[16:31]
	v_cmp_gt_f32_e32 vcc, 1.0, v244
	v_mfma_f32_32x32x16_bf16 v[16:31], v[72:75], v[100:103], v[16:31]
	v_exp_f32_e32 v72, v200
	v_exp_f32_e32 v73, v199
	v_exp_f32_e32 v74, v198
	v_exp_f32_e32 v75, v127
	v_mfma_f32_32x32x16_bf16 v[16:31], v[76:79], v[104:107], v[16:31]
	v_exp_f32_e32 v76, v125
	v_exp_f32_e32 v77, v124
	v_exp_f32_e32 v78, v123
	v_exp_f32_e32 v79, v122
	v_mfma_f32_32x32x16_bf16 v[16:31], v[112:115], v[108:111], v[16:31]
	s_cbranch_vccz .LBB0_620
	s_and_saveexec_b64 s[74:75], s[0:1]
	ds_write_b32 v179, v244 offset:128
	s_or_b64 exec, exec, s[74:75]
	s_waitcnt lgkmcnt(0)
	v_add_u32_e32 v108, s81, v178
	ds_read_b128 v[96:99], v108 offset:224
	ds_read_b128 v[100:103], v108 offset:192
	ds_read_b128 v[104:107], v108 offset:160
	ds_read_b128 v[108:111], v108 offset:128
	s_waitcnt lgkmcnt(0)
	v_pk_mul_f32 v[12:13], v[12:13], v[96:97]
	v_pk_mul_f32 v[8:9], v[8:9], v[100:101]
	v_pk_mul_f32 v[4:5], v[4:5], v[104:105]
	v_pk_mul_f32 v[14:15], v[14:15], v[98:99]
	v_pk_mul_f32 v[10:11], v[10:11], v[102:103]
	v_pk_mul_f32 v[6:7], v[6:7], v[106:107]
	v_pk_mul_f32 v[2:3], v[2:3], v[110:111]
	v_pk_mul_f32 v[0:1], v[0:1], v[108:109]
	v_pk_mul_f32 v[60:61], v[60:61], v[96:97]
	v_pk_mul_f32 v[56:57], v[56:57], v[100:101]
	v_pk_mul_f32 v[52:53], v[52:53], v[104:105]
	v_pk_mul_f32 v[62:63], v[62:63], v[98:99]
	v_pk_mul_f32 v[58:59], v[58:59], v[102:103]
	v_pk_mul_f32 v[54:55], v[54:55], v[106:107]
	v_pk_mul_f32 v[50:51], v[50:51], v[110:111]
	v_pk_mul_f32 v[48:49], v[48:49], v[108:109]
	v_pk_mul_f32 v[44:45], v[44:45], v[96:97]
	v_pk_mul_f32 v[40:41], v[40:41], v[100:101]
	v_pk_mul_f32 v[36:37], v[36:37], v[104:105]
	v_pk_mul_f32 v[46:47], v[46:47], v[98:99]
	v_pk_mul_f32 v[42:43], v[42:43], v[102:103]
	v_pk_mul_f32 v[38:39], v[38:39], v[106:107]
	v_pk_mul_f32 v[34:35], v[34:35], v[110:111]
	v_pk_mul_f32 v[32:33], v[32:33], v[108:109]
	v_pk_mul_f32 v[28:29], v[28:29], v[96:97]
	v_pk_mul_f32 v[24:25], v[24:25], v[100:101]
	v_pk_mul_f32 v[20:21], v[20:21], v[104:105]
	v_pk_mul_f32 v[30:31], v[30:31], v[98:99]
	v_pk_mul_f32 v[26:27], v[26:27], v[102:103]
	v_pk_mul_f32 v[22:23], v[22:23], v[106:107]
	v_pk_mul_f32 v[18:19], v[18:19], v[110:111]
	v_pk_mul_f32 v[16:17], v[16:17], v[108:109]
